# P4 pipelined + P5 residual epilogue: second column half's loads requested with the first half's (8 round trips per unit instead of 16)
# speedup vs baseline: 1.0081x; 1.0081x over previous
;     __device__ __forceinline__ void operator()(const f32x4 (&acc)[2][2][4][2], const Unit& u, int wr, int wc, int fr, int fq) const {
;         const int row0 = u.pm * BM + wr * 64 + fr, col0 = u.pn * BM + wc * 32 + 8 * fq;
;         if (u.part >= 0) {
;             bf16* sp = slab + ((ptrdiff_t)u.part * mk::MS - mk::MP) * (ptrdiff_t)mk::D + col0;
; #pragma unroll
;             for (int ai = 0; ai < 2; ++ai)
; #pragma unroll
;                 for (int m = 0; m < 4; ++m) { bf16* rowp = sp + (ptrdiff_t)(row0 + ai * HALF + m * 16) * mk::D;
; #pragma unroll
;                     for (int bj = 0; bj < 2; ++bj) { const f32x4 v0 = acc[ai][bj][m][0] * ascale, v1 = acc[ai][bj][m][1] * ascale;
;                         u32x4 w; w.x = mk::pk2(v0[0], v0[1]); w.y = mk::pk2(v0[2], v0[3]); w.z = mk::pk2(v1[0], v1[1]); w.w = mk::pk2(v1[2], v1[3]); *(u32x4*)(rowp + bj * HALF) = w; } }
;             return;
;         }
; #pragma unroll
;         for (int ai = 0; ai < 2; ++ai)
; #pragma unroll
;             for (int m = 0; m < 4; ++m) { const int r = row0 + ai * HALF + m * 16; const size_t off = (size_t)r * mk::D + col0; const float* gp = gate + (size_t)mk::seq_of(r) * mk::NMOD + col0;
;                 float ss = 0.f;
; #pragma unroll
;                 for (int bj = 0; bj < 2; ++bj) { const int o = bj * HALF;
;                     f32x4 x0, x1;
;                     if constexpr (XIF32) { x0 = *(const f32x4*)((const float*)xi + off + o); x1 = *(const f32x4*)((const float*)xi + off + o + 4); }
;                     else { const u32x4 w = *(const u32x4*)((const bf16*)xi + off + o);
;                         x0 = (f32x4){__uint_as_float(w.x << 16), __uint_as_float(w.x & 0xffff0000u), __uint_as_float(w.y << 16), __uint_as_float(w.y & 0xffff0000u)};
;                         x1 = (f32x4){__uint_as_float(w.z << 16), __uint_as_float(w.z & 0xffff0000u), __uint_as_float(w.w << 16), __uint_as_float(w.w & 0xffff0000u)}; }
;                     f32x4 v0 = acc[ai][bj][m][0] * ascale, v1 = acc[ai][bj][m][1] * ascale;
;                     if constexpr (MODE == 1) { v0 *= *(const f32x4*)(extra + col0 + o); v1 *= *(const f32x4*)(extra + col0 + o + 4); }
;                     const f32x4 y0 = x0 + *(const f32x4*)(gp + o) * v0, y1 = x1 + *(const f32x4*)(gp + o + 4) * v1;
.LBB0_807:
	s_lshl_b32 s10, s68, 8
	s_add_i32 s10, s10, s82
	s_nop 15
	s_nop 15
	v_or_b32_e32 v8, s10, v1
	v_lshl_or_b32 v10, s69, 8, v183
	v_or_b32_e32 v6, 16, v8
	v_or_b32_e32 v4, 32, v8
	v_or_b32_e32 v2, 48, v8
	s_mov_b64 s[60:61], -1
	s_cmp_gt_i32 s4, -1
	v_ashrrev_i32_e32 v11, 31, v10
	v_ashrrev_i32_e32 v9, 31, v8
	v_ashrrev_i32_e32 v7, 31, v6
	v_ashrrev_i32_e32 v5, 31, v4
	v_ashrrev_i32_e32 v3, 31, v2
	s_cbranch_scc1 .LBB0_810
	v_lshlrev_b64 v[12:13], 11, v[8:9]
	v_lshl_add_u64 v[16:17], v[12:13], 0, v[10:11]
	v_add_u32_e32 v12, 0xffffe000, v8
	s_ashr_i32 s10, s10, 11
	v_lshrrev_b32_e32 v12, 3, v12
	v_or_b32_e32 v12, 4, v12
	v_mov_b32_e32 v196, s10
	v_cmp_gt_i32_e32 vcc, s81, v8
	v_pk_mul_f32 v[178:179], v[160:161], s[36:37] op_sel_hi:[1,0]
	v_pk_mul_f32 v[180:181], v[158:159], s[36:37] op_sel_hi:[1,0]
	v_cndmask_b32_e32 v14, v12, v196, vcc
	v_mov_b64_e32 v[12:13], s[16:17]
	v_mad_i64_i32 v[18:19], s[52:53], v14, s87, v[12:13]
	v_lshlrev_b64 v[14:15], 2, v[10:11]
	v_readlane_b32 s40, v240, 27
	v_lshl_add_u64 v[174:175], v[18:19], 0, v[14:15]
	v_readlane_b32 s41, v240, 28
	v_pk_mul_f32 v[188:189], v[156:157], s[36:37] op_sel_hi:[1,0]
	v_pk_mul_f32 v[190:191], v[154:155], s[36:37] op_sel_hi:[1,0]
	v_lshl_add_u64 v[176:177], v[16:17], 2, s[40:41]
	global_load_dwordx4 v[18:21], v[174:175], off
	global_load_dwordx4 v[22:25], v[176:177], off
	global_load_dwordx4 v[26:29], v[176:177], off offset:16
	global_load_dwordx4 v[30:33], v[174:175], off offset:16
	global_load_dwordx4 v[200:203], v[174:175], off offset:512
	global_load_dwordx4 v[204:207], v[176:177], off offset:512
	global_load_dwordx4 v[208:211], v[176:177], off offset:528
	global_load_dwordx4 v[212:215], v[174:175], off offset:528
	v_lshl_add_u64 v[192:193], v[16:17], 1, s[8:9]
	v_cmp_gt_i32_e32 vcc, s81, v6
	v_readlane_b32 s52, v240, 39
	v_readlane_b32 s53, v240, 40
	s_movk_i32 s10, 0x1f80
	v_readlane_b32 s44, v240, 31
	v_readlane_b32 s45, v240, 32
	v_readlane_b32 s44, v240, 44
	v_readlane_b32 s42, v240, 29
	v_readlane_b32 s43, v240, 30
	v_readlane_b32 s46, v240, 33
	v_readlane_b32 s47, v240, 34
	v_readlane_b32 s48, v240, 35
	v_readlane_b32 s49, v240, 36
	v_readlane_b32 s50, v240, 37
	v_readlane_b32 s51, v240, 38
	v_readlane_b32 s54, v240, 41
	v_readlane_b32 s55, v240, 42
	v_readlane_b32 s45, v240, 45
	s_waitcnt vmcnt(4)
	v_pk_fma_f32 v[20:21], v[178:179], v[20:21], v[24:25]
	v_pk_fma_f32 v[18:19], v[180:181], v[18:19], v[22:23]
	v_pk_fma_f32 v[22:23], v[188:189], v[32:33], v[28:29]
	v_pk_fma_f32 v[24:25], v[190:191], v[30:31], v[26:27]
	v_cvt_pk_bf16_f32 v18, v18, v19
	v_cvt_pk_bf16_f32 v19, v20, v21
	v_cvt_pk_bf16_f32 v21, v22, v23
	v_add_u32_e32 v190, 0xffffe010, v8
	v_cvt_pk_bf16_f32 v20, v24, v25
	global_store_dwordx4 v[192:193], v[18:21], off
	v_lshrrev_b32_e32 v190, 3, v190
	v_pk_mul_f32 v[174:175], v[152:153], s[36:37] op_sel_hi:[1,0]
	v_pk_mul_f32 v[176:177], v[150:151], s[36:37] op_sel_hi:[1,0]
	v_or_b32_e32 v194, 4, v190
	v_pk_mul_f32 v[178:179], v[144:145], s[36:37] op_sel_hi:[1,0]
	v_pk_mul_f32 v[180:181], v[142:143], s[36:37] op_sel_hi:[1,0]
	v_cndmask_b32_e32 v194, v194, v196, vcc
	v_lshlrev_b64 v[188:189], 11, v[6:7]
	v_mad_i64_i32 v[194:195], s[52:53], v194, s87, v[12:13]
	v_lshl_add_u64 v[188:189], v[188:189], 0, v[10:11]
	v_lshl_add_u64 v[194:195], v[194:195], 0, v[14:15]
	v_lshl_add_u64 v[190:191], v[188:189], 2, s[40:41]
	v_lshl_add_u64 v[188:189], v[188:189], 1, s[8:9]
	v_cmp_gt_i32_e32 vcc, s81, v4
	s_waitcnt vmcnt(3)
	v_pk_fma_f32 v[20:21], v[174:175], v[202:203], v[206:207]
	v_pk_fma_f32 v[18:19], v[176:177], v[200:201], v[204:205]
	s_waitcnt vmcnt(1)
	v_pk_fma_f32 v[22:23], v[178:179], v[214:215], v[210:211]
	v_pk_fma_f32 v[24:25], v[180:181], v[212:213], v[208:209]
	v_cvt_pk_bf16_f32 v18, v18, v19
	v_cvt_pk_bf16_f32 v19, v20, v21
	v_cvt_pk_bf16_f32 v21, v22, v23
	v_pk_mul_f32 v[174:175], v[148:149], s[36:37] op_sel_hi:[1,0]
	v_cvt_pk_bf16_f32 v20, v24, v25
	global_store_dwordx4 v[192:193], v[18:21], off offset:256
	global_load_dwordx4 v[18:21], v[194:195], off
	global_load_dwordx4 v[22:25], v[190:191], off
	global_load_dwordx4 v[26:29], v[190:191], off offset:16
	global_load_dwordx4 v[30:33], v[194:195], off offset:16
	global_load_dwordx4 v[200:203], v[194:195], off offset:512
	global_load_dwordx4 v[204:207], v[190:191], off offset:512
	global_load_dwordx4 v[208:211], v[190:191], off offset:528
	global_load_dwordx4 v[212:215], v[194:195], off offset:528
	v_pk_mul_f32 v[176:177], v[146:147], s[36:37] op_sel_hi:[1,0]
	v_pk_mul_f32 v[178:179], v[140:141], s[36:37] op_sel_hi:[1,0]
	v_pk_mul_f32 v[180:181], v[138:139], s[36:37] op_sel_hi:[1,0]
	v_add_u32_e32 v192, 0xffffe020, v8
	v_lshrrev_b32_e32 v192, 3, v192
	s_waitcnt vmcnt(6)
	v_pk_fma_f32 v[20:21], v[174:175], v[20:21], v[24:25]
	v_pk_fma_f32 v[18:19], v[176:177], v[18:19], v[22:23]
	s_waitcnt vmcnt(4)
	v_pk_fma_f32 v[22:23], v[178:179], v[32:33], v[28:29]
	v_pk_fma_f32 v[24:25], v[180:181], v[30:31], v[26:27]
	v_cvt_pk_bf16_f32 v18, v18, v19
	v_cvt_pk_bf16_f32 v19, v20, v21
	v_cvt_pk_bf16_f32 v21, v22, v23
	v_pk_mul_f32 v[174:175], v[136:137], s[36:37] op_sel_hi:[1,0]
	v_cvt_pk_bf16_f32 v20, v24, v25
	global_store_dwordx4 v[188:189], v[18:21], off
	v_pk_mul_f32 v[176:177], v[134:135], s[36:37] op_sel_hi:[1,0]
	v_add_u32_e32 v194, 4, v192
	v_pk_mul_f32 v[178:179], v[128:129], s[36:37] op_sel_hi:[1,0]
	v_pk_mul_f32 v[180:181], v[126:127], s[36:37] op_sel_hi:[1,0]
	v_cndmask_b32_e32 v194, v194, v196, vcc
	v_lshlrev_b64 v[190:191], 11, v[4:5]
	v_mad_i64_i32 v[194:195], s[52:53], v194, s87, v[12:13]
	v_lshl_add_u64 v[190:191], v[190:191], 0, v[10:11]
	v_lshl_add_u64 v[194:195], v[194:195], 0, v[14:15]
	v_lshl_add_u64 v[192:193], v[190:191], 2, s[40:41]
	v_cmp_gt_i32_e32 vcc, s81, v2
	s_waitcnt vmcnt(3)
; __device__ __forceinline__ unsigned pk2(float lo, float hi) { unsigned r; asm("v_cvt_pk_bf16_f32 %0, %1, %2" : "=v"(r) : "v"(lo), "v"(hi)); return r; }
;     __device__ __forceinline__ void operator()(const f32x4 (&acc)[2][2][4][2], const Unit& u, int wr, int wc, int fr, int fq) const {
;     ...
;         for (int ai = 0; ai < 2; ++ai)
; #pragma unroll
;             for (int m = 0; m < 4; ++m) { const int r = row0 + ai * HALF + m * 16; const size_t off = (size_t)r * mk::D + col0; const float* gp = gate + (size_t)mk::seq_of(r) * mk::NMOD + col0;
;                 float ss = 0.f;
; #pragma unroll
;                 for (int bj = 0; bj < 2; ++bj) { const int o = bj * HALF;
;                     f32x4 x0, x1;
;                     if constexpr (XIF32) { x0 = *(const f32x4*)((const float*)xi + off + o); x1 = *(const f32x4*)((const float*)xi + off + o + 4); }
;                     else { const u32x4 w = *(const u32x4*)((const bf16*)xi + off + o);
;                         x0 = (f32x4){__uint_as_float(w.x << 16), __uint_as_float(w.x & 0xffff0000u), __uint_as_float(w.y << 16), __uint_as_float(w.y & 0xffff0000u)};
;                         x1 = (f32x4){__uint_as_float(w.z << 16), __uint_as_float(w.z & 0xffff0000u), __uint_as_float(w.w << 16), __uint_as_float(w.w & 0xffff0000u)}; }
;                     f32x4 v0 = acc[ai][bj][m][0] * ascale, v1 = acc[ai][bj][m][1] * ascale;
;                     if constexpr (MODE == 1) { v0 *= *(const f32x4*)(extra + col0 + o); v1 *= *(const f32x4*)(extra + col0 + o + 4); }
;                     const f32x4 y0 = x0 + *(const f32x4*)(gp + o) * v0, y1 = x1 + *(const f32x4*)(gp + o + 4) * v1;
;                     u32x4 w; w.x = mk::pk2(y0[0], y0[1]); w.y = mk::pk2(y0[2], y0[3]); w.z = mk::pk2(y1[0], y1[1]); w.w = mk::pk2(y1[2], y1[3]); *(u32x4*)(xo + off + o) = w;
	v_pk_fma_f32 v[20:21], v[174:175], v[202:203], v[206:207]
	v_pk_fma_f32 v[18:19], v[176:177], v[200:201], v[204:205]
	s_waitcnt vmcnt(1)
	v_pk_fma_f32 v[22:23], v[178:179], v[214:215], v[210:211]
	v_pk_fma_f32 v[24:25], v[180:181], v[212:213], v[208:209]
	v_cvt_pk_bf16_f32 v18, v18, v19
	v_cvt_pk_bf16_f32 v19, v20, v21
	v_cvt_pk_bf16_f32 v21, v22, v23
	v_pk_mul_f32 v[174:175], v[132:133], s[36:37] op_sel_hi:[1,0]
	v_cvt_pk_bf16_f32 v20, v24, v25
	global_store_dwordx4 v[188:189], v[18:21], off offset:256
	global_load_dwordx4 v[18:21], v[194:195], off
	global_load_dwordx4 v[22:25], v[192:193], off
	global_load_dwordx4 v[26:29], v[192:193], off offset:16
	global_load_dwordx4 v[30:33], v[194:195], off offset:16
	global_load_dwordx4 v[200:203], v[194:195], off offset:512
	global_load_dwordx4 v[204:207], v[192:193], off offset:512
	global_load_dwordx4 v[208:211], v[192:193], off offset:528
	global_load_dwordx4 v[212:215], v[194:195], off offset:528
	v_pk_mul_f32 v[176:177], v[130:131], s[36:37] op_sel_hi:[1,0]
	v_pk_mul_f32 v[178:179], v[124:125], s[36:37] op_sel_hi:[1,0]
	v_pk_mul_f32 v[180:181], v[122:123], s[36:37] op_sel_hi:[1,0]
	v_lshl_add_u64 v[188:189], v[190:191], 1, s[8:9]
	v_lshlrev_b64 v[190:191], 11, v[2:3]
	v_lshl_add_u64 v[190:191], v[190:191], 0, v[10:11]
	s_waitcnt vmcnt(6)
	v_pk_fma_f32 v[20:21], v[174:175], v[20:21], v[24:25]
	v_pk_fma_f32 v[18:19], v[176:177], v[18:19], v[22:23]
	s_waitcnt vmcnt(4)
	v_pk_fma_f32 v[22:23], v[178:179], v[32:33], v[28:29]
	v_pk_fma_f32 v[24:25], v[180:181], v[30:31], v[26:27]
	v_cvt_pk_bf16_f32 v18, v18, v19
	v_cvt_pk_bf16_f32 v19, v20, v21
	v_cvt_pk_bf16_f32 v21, v22, v23
	v_pk_mul_f32 v[174:175], v[120:121], s[36:37] op_sel_hi:[1,0]
	v_cvt_pk_bf16_f32 v20, v24, v25
	global_store_dwordx4 v[188:189], v[18:21], off
	v_add_u32_e32 v192, 0xffffe030, v8
	v_lshrrev_b32_e32 v192, 3, v192
	v_pk_mul_f32 v[176:177], v[118:119], s[36:37] op_sel_hi:[1,0]
	v_add_u32_e32 v194, 4, v192
	v_pk_mul_f32 v[178:179], v[112:113], s[36:37] op_sel_hi:[1,0]
	v_pk_mul_f32 v[180:181], v[110:111], s[36:37] op_sel_hi:[1,0]
	v_cndmask_b32_e32 v194, v194, v196, vcc
	v_mad_i64_i32 v[194:195], s[52:53], v194, s87, v[12:13]
	v_lshl_add_u64 v[194:195], v[194:195], 0, v[14:15]
	v_lshl_add_u64 v[192:193], v[190:191], 2, s[40:41]
	v_cmp_gt_i32_e32 vcc, s10, v8
	s_movk_i32 s10, 0x1f70
	s_waitcnt vmcnt(3)
	v_pk_fma_f32 v[20:21], v[174:175], v[202:203], v[206:207]
	v_pk_fma_f32 v[18:19], v[176:177], v[200:201], v[204:205]
	s_waitcnt vmcnt(1)
	v_pk_fma_f32 v[22:23], v[178:179], v[214:215], v[210:211]
	v_pk_fma_f32 v[24:25], v[180:181], v[212:213], v[208:209]
	v_cvt_pk_bf16_f32 v18, v18, v19
	v_cvt_pk_bf16_f32 v19, v20, v21
	v_cvt_pk_bf16_f32 v21, v22, v23
	v_pk_mul_f32 v[174:175], v[116:117], s[36:37] op_sel_hi:[1,0]
	v_cvt_pk_bf16_f32 v20, v24, v25
	global_store_dwordx4 v[188:189], v[18:21], off offset:256
	global_load_dwordx4 v[18:21], v[194:195], off
	global_load_dwordx4 v[22:25], v[192:193], off
	global_load_dwordx4 v[26:29], v[192:193], off offset:16
	global_load_dwordx4 v[30:33], v[194:195], off offset:16
	global_load_dwordx4 v[200:203], v[194:195], off offset:512
	global_load_dwordx4 v[204:207], v[192:193], off offset:512
	global_load_dwordx4 v[208:211], v[192:193], off offset:528
	global_load_dwordx4 v[212:215], v[194:195], off offset:528
	v_pk_mul_f32 v[176:177], v[114:115], s[36:37] op_sel_hi:[1,0]
	v_pk_mul_f32 v[178:179], v[108:109], s[36:37] op_sel_hi:[1,0]
	v_pk_mul_f32 v[180:181], v[106:107], s[36:37] op_sel_hi:[1,0]
	v_lshl_add_u64 v[188:189], v[190:191], 1, s[8:9]
	v_add_u32_e32 v190, 0x80, v8
	v_ashrrev_i32_e32 v196, 11, v190
	v_ashrrev_i32_e32 v191, 31, v190
	v_lshlrev_b64 v[190:191], 11, v[190:191]
	v_lshl_add_u64 v[190:191], v[190:191], 0, v[10:11]
	s_waitcnt vmcnt(6)
	v_pk_fma_f32 v[20:21], v[174:175], v[20:21], v[24:25]
	v_pk_fma_f32 v[18:19], v[176:177], v[18:19], v[22:23]
	s_waitcnt vmcnt(4)
	v_pk_fma_f32 v[22:23], v[178:179], v[32:33], v[28:29]
	v_pk_fma_f32 v[24:25], v[180:181], v[30:31], v[26:27]
	v_cvt_pk_bf16_f32 v18, v18, v19
	v_cvt_pk_bf16_f32 v19, v20, v21
	v_cvt_pk_bf16_f32 v21, v22, v23
	v_pk_mul_f32 v[174:175], v[104:105], s[36:37] op_sel_hi:[1,0]
	v_cvt_pk_bf16_f32 v20, v24, v25
	global_store_dwordx4 v[188:189], v[18:21], off
	v_add_u32_e32 v192, 0xffffe080, v8
	v_lshrrev_b32_e32 v192, 3, v192
	v_pk_mul_f32 v[176:177], v[102:103], s[36:37] op_sel_hi:[1,0]
	v_or_b32_e32 v192, 4, v192
	v_pk_mul_f32 v[178:179], v[100:101], s[36:37] op_sel_hi:[1,0]
	v_pk_mul_f32 v[180:181], v[98:99], s[36:37] op_sel_hi:[1,0]
	v_cndmask_b32_e32 v192, v192, v196, vcc
	v_mad_i64_i32 v[192:193], s[52:53], v192, s87, v[12:13]
	v_lshl_add_u64 v[192:193], v[192:193], 0, v[14:15]
	v_lshl_add_u64 v[194:195], v[190:191], 2, s[40:41]
	v_cmp_gt_i32_e32 vcc, s10, v8
	s_mov_b64 s[52:53], 0x48000
	s_movk_i32 s10, 0x1f60
	s_waitcnt vmcnt(3)
	v_pk_fma_f32 v[20:21], v[174:175], v[202:203], v[206:207]
	v_pk_fma_f32 v[18:19], v[176:177], v[200:201], v[204:205]
	s_waitcnt vmcnt(1)
	v_pk_fma_f32 v[22:23], v[178:179], v[214:215], v[210:211]
	v_pk_fma_f32 v[24:25], v[180:181], v[212:213], v[208:209]
	v_cvt_pk_bf16_f32 v18, v18, v19
	v_cvt_pk_bf16_f32 v19, v20, v21
	v_cvt_pk_bf16_f32 v21, v22, v23
	v_pk_mul_f32 v[174:175], v[96:97], s[36:37] op_sel_hi:[1,0]
	v_cvt_pk_bf16_f32 v20, v24, v25
	global_store_dwordx4 v[188:189], v[18:21], off offset:256
	global_load_dwordx4 v[18:21], v[192:193], off
	global_load_dwordx4 v[22:25], v[194:195], off
	global_load_dwordx4 v[26:29], v[194:195], off offset:16
	global_load_dwordx4 v[30:33], v[192:193], off offset:16
	global_load_dwordx4 v[200:203], v[192:193], off offset:512
	global_load_dwordx4 v[204:207], v[194:195], off offset:512
	global_load_dwordx4 v[208:211], v[194:195], off offset:528
	global_load_dwordx4 v[212:215], v[192:193], off offset:528
	v_pk_mul_f32 v[176:177], v[94:95], s[36:37] op_sel_hi:[1,0]
	v_pk_mul_f32 v[178:179], v[92:93], s[36:37] op_sel_hi:[1,0]
	v_pk_mul_f32 v[180:181], v[90:91], s[36:37] op_sel_hi:[1,0]
	v_lshl_add_u64 v[188:189], v[190:191], 1, s[8:9]
	v_add_u32_e32 v190, 0xffffe090, v8
	s_waitcnt vmcnt(6)
; __device__ __forceinline__ unsigned pk2(float lo, float hi) { unsigned r; asm("v_cvt_pk_bf16_f32 %0, %1, %2" : "=v"(r) : "v"(lo), "v"(hi)); return r; }
;     __device__ __forceinline__ void operator()(const f32x4 (&acc)[2][2][4][2], const Unit& u, int wr, int wc, int fr, int fq) const {
;     ...
;         for (int ai = 0; ai < 2; ++ai)
; #pragma unroll
;             for (int m = 0; m < 4; ++m) { const int r = row0 + ai * HALF + m * 16; const size_t off = (size_t)r * mk::D + col0; const float* gp = gate + (size_t)mk::seq_of(r) * mk::NMOD + col0;
;                 float ss = 0.f;
; #pragma unroll
;                 for (int bj = 0; bj < 2; ++bj) { const int o = bj * HALF;
;                     f32x4 x0, x1;
;                     if constexpr (XIF32) { x0 = *(const f32x4*)((const float*)xi + off + o); x1 = *(const f32x4*)((const float*)xi + off + o + 4); }
;                     else { const u32x4 w = *(const u32x4*)((const bf16*)xi + off + o);
;                         x0 = (f32x4){__uint_as_float(w.x << 16), __uint_as_float(w.x & 0xffff0000u), __uint_as_float(w.y << 16), __uint_as_float(w.y & 0xffff0000u)};
;                         x1 = (f32x4){__uint_as_float(w.z << 16), __uint_as_float(w.z & 0xffff0000u), __uint_as_float(w.w << 16), __uint_as_float(w.w & 0xffff0000u)}; }
;                     f32x4 v0 = acc[ai][bj][m][0] * ascale, v1 = acc[ai][bj][m][1] * ascale;
;                     if constexpr (MODE == 1) { v0 *= *(const f32x4*)(extra + col0 + o); v1 *= *(const f32x4*)(extra + col0 + o + 4); }
;                     const f32x4 y0 = x0 + *(const f32x4*)(gp + o) * v0, y1 = x1 + *(const f32x4*)(gp + o + 4) * v1;
;                     u32x4 w; w.x = mk::pk2(y0[0], y0[1]); w.y = mk::pk2(y0[2], y0[3]); w.z = mk::pk2(y1[0], y1[1]); w.w = mk::pk2(y1[2], y1[3]); *(u32x4*)(xo + off + o) = w;
	v_pk_fma_f32 v[20:21], v[174:175], v[20:21], v[24:25]
	v_pk_fma_f32 v[18:19], v[176:177], v[18:19], v[22:23]
	s_waitcnt vmcnt(4)
	v_pk_fma_f32 v[22:23], v[178:179], v[32:33], v[28:29]
	v_pk_fma_f32 v[24:25], v[180:181], v[30:31], v[26:27]
	v_cvt_pk_bf16_f32 v18, v18, v19
	v_cvt_pk_bf16_f32 v19, v20, v21
	v_cvt_pk_bf16_f32 v21, v22, v23
	v_pk_mul_f32 v[174:175], v[88:89], s[36:37] op_sel_hi:[1,0]
	v_cvt_pk_bf16_f32 v20, v24, v25
	global_store_dwordx4 v[188:189], v[18:21], off
	v_lshrrev_b32_e32 v192, 3, v190
	v_pk_mul_f32 v[176:177], v[86:87], s[36:37] op_sel_hi:[1,0]
	v_or_b32_e32 v192, 4, v192
	v_pk_mul_f32 v[178:179], v[80:81], s[36:37] op_sel_hi:[1,0]
	v_pk_mul_f32 v[180:181], v[78:79], s[36:37] op_sel_hi:[1,0]
	v_cndmask_b32_e32 v194, v192, v196, vcc
	v_lshl_add_u64 v[190:191], v[16:17], 0, s[52:53]
	v_mad_i64_i32 v[194:195], s[52:53], v194, s87, v[12:13]
	v_lshl_add_u64 v[194:195], v[194:195], 0, v[14:15]
	v_lshl_add_u64 v[192:193], v[190:191], 2, s[40:41]
	v_cmp_gt_i32_e32 vcc, s10, v8
	s_mov_b64 s[52:53], 0x50000
	s_movk_i32 s10, 0x1f50
	s_waitcnt vmcnt(3)
	v_pk_fma_f32 v[20:21], v[174:175], v[202:203], v[206:207]
	v_pk_fma_f32 v[18:19], v[176:177], v[200:201], v[204:205]
	s_waitcnt vmcnt(1)
	v_pk_fma_f32 v[22:23], v[178:179], v[214:215], v[210:211]
	v_pk_fma_f32 v[24:25], v[180:181], v[212:213], v[208:209]
	v_cvt_pk_bf16_f32 v18, v18, v19
	v_cvt_pk_bf16_f32 v19, v20, v21
	v_cvt_pk_bf16_f32 v21, v22, v23
	v_pk_mul_f32 v[174:175], v[84:85], s[36:37] op_sel_hi:[1,0]
	v_cvt_pk_bf16_f32 v20, v24, v25
	global_store_dwordx4 v[188:189], v[18:21], off offset:256
	global_load_dwordx4 v[18:21], v[194:195], off
	global_load_dwordx4 v[22:25], v[192:193], off
	global_load_dwordx4 v[26:29], v[192:193], off offset:16
	global_load_dwordx4 v[30:33], v[194:195], off offset:16
	global_load_dwordx4 v[200:203], v[194:195], off offset:512
	global_load_dwordx4 v[204:207], v[192:193], off offset:512
	global_load_dwordx4 v[208:211], v[192:193], off offset:528
	global_load_dwordx4 v[212:215], v[194:195], off offset:528
	v_pk_mul_f32 v[176:177], v[82:83], s[36:37] op_sel_hi:[1,0]
	v_pk_mul_f32 v[178:179], v[76:77], s[36:37] op_sel_hi:[1,0]
	v_pk_mul_f32 v[180:181], v[74:75], s[36:37] op_sel_hi:[1,0]
	v_lshl_add_u64 v[188:189], v[190:191], 1, s[8:9]
	v_add_u32_e32 v190, 0xffffe0a0, v8
	s_waitcnt vmcnt(6)
	v_pk_fma_f32 v[20:21], v[174:175], v[20:21], v[24:25]
	v_pk_fma_f32 v[18:19], v[176:177], v[18:19], v[22:23]
	s_waitcnt vmcnt(4)
	v_pk_fma_f32 v[22:23], v[178:179], v[32:33], v[28:29]
	v_pk_fma_f32 v[24:25], v[180:181], v[30:31], v[26:27]
	v_cvt_pk_bf16_f32 v18, v18, v19
	v_cvt_pk_bf16_f32 v19, v20, v21
	v_cvt_pk_bf16_f32 v21, v22, v23
	v_pk_mul_f32 v[174:175], v[72:73], s[36:37] op_sel_hi:[1,0]
	v_cvt_pk_bf16_f32 v20, v24, v25
	global_store_dwordx4 v[188:189], v[18:21], off
	v_lshrrev_b32_e32 v192, 3, v190
	v_pk_mul_f32 v[176:177], v[70:71], s[36:37] op_sel_hi:[1,0]
	v_add_u32_e32 v192, 4, v192
	v_pk_mul_f32 v[178:179], v[64:65], s[36:37] op_sel_hi:[1,0]
	v_pk_mul_f32 v[180:181], v[62:63], s[36:37] op_sel_hi:[1,0]
	v_cndmask_b32_e32 v194, v192, v196, vcc
	v_lshl_add_u64 v[190:191], v[16:17], 0, s[52:53]
	v_mad_i64_i32 v[194:195], s[52:53], v194, s87, v[12:13]
	v_lshl_add_u64 v[194:195], v[194:195], 0, v[14:15]
	v_lshl_add_u64 v[192:193], v[190:191], 2, s[40:41]
	s_mov_b64 s[52:53], 0x58000
	v_cmp_gt_i32_e32 vcc, s10, v8
	s_waitcnt vmcnt(3)
	v_pk_fma_f32 v[20:21], v[174:175], v[202:203], v[206:207]
	v_pk_fma_f32 v[18:19], v[176:177], v[200:201], v[204:205]
	s_waitcnt vmcnt(1)
	v_pk_fma_f32 v[22:23], v[178:179], v[214:215], v[210:211]
	v_pk_fma_f32 v[24:25], v[180:181], v[212:213], v[208:209]
	v_cvt_pk_bf16_f32 v18, v18, v19
	v_cvt_pk_bf16_f32 v19, v20, v21
	v_cvt_pk_bf16_f32 v21, v22, v23
	v_pk_mul_f32 v[174:175], v[68:69], s[36:37] op_sel_hi:[1,0]
	v_cvt_pk_bf16_f32 v20, v24, v25
	global_store_dwordx4 v[188:189], v[18:21], off offset:256
	global_load_dwordx4 v[18:21], v[194:195], off
	global_load_dwordx4 v[22:25], v[192:193], off
	global_load_dwordx4 v[26:29], v[192:193], off offset:16
	global_load_dwordx4 v[30:33], v[194:195], off offset:16
	global_load_dwordx4 v[200:203], v[194:195], off offset:512
	global_load_dwordx4 v[204:207], v[192:193], off offset:512
	global_load_dwordx4 v[208:211], v[192:193], off offset:528
	global_load_dwordx4 v[212:215], v[194:195], off offset:528
	v_pk_mul_f32 v[176:177], v[66:67], s[36:37] op_sel_hi:[1,0]
	v_pk_mul_f32 v[178:179], v[60:61], s[36:37] op_sel_hi:[1,0]
	v_pk_mul_f32 v[180:181], v[58:59], s[36:37] op_sel_hi:[1,0]
	v_lshl_add_u64 v[188:189], v[190:191], 1, s[8:9]
	v_add_u32_e32 v190, 0xffffe0b0, v8
	s_waitcnt vmcnt(6)
; __device__ __forceinline__ unsigned pk2(float lo, float hi) { unsigned r; asm("v_cvt_pk_bf16_f32 %0, %1, %2" : "=v"(r) : "v"(lo), "v"(hi)); return r; }
;     __device__ __forceinline__ void operator()(const f32x4 (&acc)[2][2][4][2], const Unit& u, int wr, int wc, int fr, int fq) const {
;     ...
;         for (int ai = 0; ai < 2; ++ai)
; #pragma unroll
;             for (int m = 0; m < 4; ++m) { const int r = row0 + ai * HALF + m * 16; const size_t off = (size_t)r * mk::D + col0; const float* gp = gate + (size_t)mk::seq_of(r) * mk::NMOD + col0;
;                 float ss = 0.f;
; #pragma unroll
;                 for (int bj = 0; bj < 2; ++bj) { const int o = bj * HALF;
;                     f32x4 x0, x1;
;                     if constexpr (XIF32) { x0 = *(const f32x4*)((const float*)xi + off + o); x1 = *(const f32x4*)((const float*)xi + off + o + 4); }
;                     else { const u32x4 w = *(const u32x4*)((const bf16*)xi + off + o);
;                         x0 = (f32x4){__uint_as_float(w.x << 16), __uint_as_float(w.x & 0xffff0000u), __uint_as_float(w.y << 16), __uint_as_float(w.y & 0xffff0000u)};
;                         x1 = (f32x4){__uint_as_float(w.z << 16), __uint_as_float(w.z & 0xffff0000u), __uint_as_float(w.w << 16), __uint_as_float(w.w & 0xffff0000u)}; }
;                     f32x4 v0 = acc[ai][bj][m][0] * ascale, v1 = acc[ai][bj][m][1] * ascale;
;                     if constexpr (MODE == 1) { v0 *= *(const f32x4*)(extra + col0 + o); v1 *= *(const f32x4*)(extra + col0 + o + 4); }
;                     const f32x4 y0 = x0 + *(const f32x4*)(gp + o) * v0, y1 = x1 + *(const f32x4*)(gp + o + 4) * v1;
;                     u32x4 w; w.x = mk::pk2(y0[0], y0[1]); w.y = mk::pk2(y0[2], y0[3]); w.z = mk::pk2(y1[0], y1[1]); w.w = mk::pk2(y1[2], y1[3]); *(u32x4*)(xo + off + o) = w;
	v_pk_fma_f32 v[20:21], v[174:175], v[20:21], v[24:25]
	v_pk_fma_f32 v[18:19], v[176:177], v[18:19], v[22:23]
	s_waitcnt vmcnt(4)
	v_pk_fma_f32 v[22:23], v[178:179], v[32:33], v[28:29]
	v_pk_fma_f32 v[24:25], v[180:181], v[30:31], v[26:27]
	v_cvt_pk_bf16_f32 v18, v18, v19
	v_cvt_pk_bf16_f32 v19, v20, v21
	v_cvt_pk_bf16_f32 v21, v22, v23
	v_pk_mul_f32 v[174:175], v[56:57], s[36:37] op_sel_hi:[1,0]
	v_cvt_pk_bf16_f32 v20, v24, v25
	global_store_dwordx4 v[188:189], v[18:21], off
	v_lshrrev_b32_e32 v192, 3, v190
	v_lshl_add_u64 v[190:191], v[16:17], 0, s[52:53]
	v_add_u32_e32 v16, 4, v192
	v_cndmask_b32_e32 v16, v16, v196, vcc
	v_pk_mul_f32 v[176:177], v[54:55], s[36:37] op_sel_hi:[1,0]
	v_mad_i64_i32 v[12:13], s[52:53], v16, s87, v[12:13]
	v_pk_mul_f32 v[178:179], v[48:49], s[36:37] op_sel_hi:[1,0]
	v_pk_mul_f32 v[180:181], v[46:47], s[36:37] op_sel_hi:[1,0]
	v_lshl_add_u64 v[194:195], v[12:13], 0, v[14:15]
	v_lshl_add_u64 v[192:193], v[190:191], 2, s[40:41]
	s_waitcnt vmcnt(3)
	v_pk_fma_f32 v[14:15], v[174:175], v[202:203], v[206:207]
	v_pk_fma_f32 v[12:13], v[176:177], v[200:201], v[204:205]
	s_waitcnt vmcnt(1)
	v_pk_fma_f32 v[16:17], v[178:179], v[214:215], v[210:211]
	v_pk_fma_f32 v[18:19], v[180:181], v[212:213], v[208:209]
	v_cvt_pk_bf16_f32 v12, v12, v13
	v_cvt_pk_bf16_f32 v13, v14, v15
	v_cvt_pk_bf16_f32 v15, v16, v17
	v_pk_mul_f32 v[28:29], v[52:53], s[36:37] op_sel_hi:[1,0]
	v_cvt_pk_bf16_f32 v14, v18, v19
	global_store_dwordx4 v[188:189], v[12:15], off offset:256
	global_load_dwordx4 v[12:15], v[194:195], off
	global_load_dwordx4 v[16:19], v[192:193], off
	global_load_dwordx4 v[20:23], v[192:193], off offset:16
	global_load_dwordx4 v[24:27], v[194:195], off offset:16
	global_load_dwordx4 v[200:203], v[194:195], off offset:512
	global_load_dwordx4 v[204:207], v[192:193], off offset:512
	global_load_dwordx4 v[208:211], v[192:193], off offset:528
	global_load_dwordx4 v[212:215], v[194:195], off offset:528
	v_pk_mul_f32 v[30:31], v[50:51], s[36:37] op_sel_hi:[1,0]
	v_pk_mul_f32 v[32:33], v[44:45], s[36:37] op_sel_hi:[1,0]
	v_pk_mul_f32 v[174:175], v[42:43], s[36:37] op_sel_hi:[1,0]
	v_lshl_add_u64 v[176:177], v[190:191], 1, s[8:9]
	s_waitcnt vmcnt(6)
	v_pk_fma_f32 v[14:15], v[28:29], v[14:15], v[18:19]
	v_pk_fma_f32 v[12:13], v[30:31], v[12:13], v[16:17]
	s_waitcnt vmcnt(4)
	v_pk_fma_f32 v[16:17], v[32:33], v[26:27], v[22:23]
	v_pk_fma_f32 v[18:19], v[174:175], v[24:25], v[20:21]
	v_cvt_pk_bf16_f32 v12, v12, v13
	v_cvt_pk_bf16_f32 v13, v14, v15
	v_cvt_pk_bf16_f32 v15, v16, v17
	v_pk_mul_f32 v[28:29], v[40:41], s[36:37] op_sel_hi:[1,0]
	v_cvt_pk_bf16_f32 v14, v18, v19
	global_store_dwordx4 v[176:177], v[12:15], off
	v_pk_mul_f32 v[30:31], v[38:39], s[36:37] op_sel_hi:[1,0]
	v_pk_mul_f32 v[32:33], v[36:37], s[36:37] op_sel_hi:[1,0]
	v_pk_mul_f32 v[174:175], v[34:35], s[36:37] op_sel_hi:[1,0]
	s_waitcnt vmcnt(3)
	v_pk_fma_f32 v[14:15], v[28:29], v[202:203], v[206:207]
	v_pk_fma_f32 v[12:13], v[30:31], v[200:201], v[204:205]
	s_waitcnt vmcnt(1)
	v_pk_fma_f32 v[16:17], v[32:33], v[214:215], v[210:211]
	v_pk_fma_f32 v[18:19], v[174:175], v[212:213], v[208:209]
	v_cvt_pk_bf16_f32 v12, v12, v13
	v_cvt_pk_bf16_f32 v13, v14, v15
	v_cvt_pk_bf16_f32 v15, v16, v17
	s_nop 0
	v_cvt_pk_bf16_f32 v14, v18, v19
	global_store_dwordx4 v[176:177], v[12:15], off offset:256
	s_cbranch_execz .LBB0_811
.LBB0_809:
	s_andn2_b64 vcc, exec, s[62:63]
	s_mov_b64 s[42:43], -1
	s_cbranch_vccnz .LBB0_793
	s_branch .LBB0_812
	s_nop 0
	s_nop 0
	s_nop 0
	s_nop 0
	s_nop 0
	s_nop 0
	s_nop 0
	s_nop 0
